# LDS-DMA C loop with counted lgkmcnt waits (V fragments no longer waited at slot start)
# baseline (speedup 1.0000x reference)
; DI float ex2(float x) { return __builtin_amdgcn_exp2f(x); }
; #define MFMA32(a, b, c) __builtin_amdgcn_mfma_f32_32x32x16_bf16((a), (b), (c), 0, 0, 0)
; template <int MODE>
; DI void attn_unit(unsigned char* lds, const AttnParams& ap, int b, int h, int qb, int tid) {
;     ...
;     for (int c = 0; c < NCH; ++c) { *(u32x4*)(Ks0 + (c * 64 + lrow) * 72 + 8 * lch) = kreg[c]; *(u32x4*)(Vs0 + (c * 64 + lrow) * 72 + 8 * lch) = vreg[c]; }
;     __syncthreads();
;     if (n + NCH < ntiles) {
; #pragma unroll
;       for (int c = 0; c < NCH; ++c) { const int jn = (MODE == 2) ? jb - NCH - c : jb + NCH + c; kreg[c] = *(const u32x4*)(kg + (size_t)jn * 64 * PLD); vreg[c] = *(const u32x4*)(vg + (size_t)jn * 4096); } }
; #pragma unroll
;     for (int c = 0; c < NCH; ++c) {
;     const int j = (MODE == 2) ? jb - c : jb + c;
;     const bf16_t* Ks = Ks0 + c * 64 * 72; const bf16_t* Vs = Vs0 + c * 64 * 72;
;     const bool active = (j <= cw) && (MODE != 0 || j >= cw - 8);
;     if (!active) continue;
;     if (MODE == 2 && D_EARLY && wdone) continue;
;     if (MODE == 1) {
; #pragma unroll
;       for (int kh = 0; kh < 2; ++kh) {
;         const bf16_t* kb = Ks + (32 * kh + r32) * 72 + 8 * hi;
;         bf16x8 p0[2], p1[2];
;         { f32x16 s0 = splat16(ap.negM);
;           s0 = MFMA32(*(const bf16x8*)(kb), qf[0], s0); s0 = MFMA32(*(const bf16x8*)(kb + 16), qf[1], s0);
; #pragma unroll
;           for (int i = 0; i < 16; ++i) { s0[i] = ex2(s0[i]); l0 += s0[i]; }
;           p0[0] = pack8(s0, 0); p0[1] = pack8(s0, 1); }
;         { f32x16 s1 = splat16(ap.negM);
;           s1 = MFMA32(*(const bf16x8*)(kb + 32), qf[2], s1); s1 = MFMA32(*(const bf16x8*)(kb + 48), qf[3], s1);
; #pragma unroll
;           for (int i = 0; i < 16; ++i) { s1[i] = ex2(s1[i]); l1 += s1[i]; }
;           p1[0] = pack8(s1, 0); p1[1] = pack8(s1, 1); }
; #pragma unroll
;         for (int kk = 0; kk < 2; ++kk) {
; #pragma unroll
;           for (int eb = 0; eb < 2; ++eb) { const bf16_t* vb = Vs + (32 * eb + r32) * 72 + 32 * kh + 16 * kk + 8 * hi; const bf16x8 vf = *(const bf16x8*)vb;
;             O0[eb] = MFMA32(vf, p0[kk], O0[eb]); O1[eb] = MFMA32(vf, p1[kk], O1[eb]); } }
.Lc_tile_ph0:
	s_add_i32 m0, s0, 32768
	s_nop 0
	global_load_lds_dwordx4 v32, s[2:3]
	s_add_i32 m0, s0, 40960
	s_nop 0
	global_load_lds_dwordx4 v157, s[10:11]
	s_add_u32 s2, s2, 0x68800
	s_addc_u32 s3, s3, 0
	s_add_u32 s10, s10, 0x2000
	s_addc_u32 s11, s11, 0
	s_waitcnt lgkmcnt(0)
	v_mfma_f32_32x32x16_bf16 v[116:131], v[166:169], v[38:41], v[48:63]
	v_exp_f32_e32 v96, v96
	v_exp_f32_e32 v97, v97
	v_exp_f32_e32 v98, v98
	v_exp_f32_e32 v99, v99
	v_mfma_f32_32x32x16_bf16 v[116:131], v[170:173], v[34:37], v[116:131]
	v_exp_f32_e32 v100, v100
	v_exp_f32_e32 v101, v101
	v_exp_f32_e32 v102, v102
	v_exp_f32_e32 v103, v103
	ds_read_b128 v[166:169], v146 offset:4096
	ds_read_b128 v[170:173], v147 offset:4096
	v_mfma_f32_32x32x16_bf16 v[80:95], v[174:177], v[158:161], v[80:95]
	v_exp_f32_e32 v104, v104
	v_exp_f32_e32 v105, v105
	v_add_f32_e32 v141, v141, v96
	v_add_f32_e32 v150, v150, v97
	v_add_f32_e32 v141, v141, v98
	v_add_f32_e32 v150, v150, v99
	v_mfma_f32_32x32x16_bf16 v[16:31], v[182:185], v[158:161], v[16:31]
	v_exp_f32_e32 v106, v106
	v_exp_f32_e32 v107, v107
	v_cvt_pk_bf16_f32 v158, v96, v97
	v_cvt_pk_bf16_f32 v159, v98, v99
	v_add_f32_e32 v141, v141, v100
	v_add_f32_e32 v150, v150, v101
	v_mfma_f32_32x32x16_bf16 v[80:95], v[178:181], v[162:165], v[80:95]
	v_exp_f32_e32 v108, v108
	v_exp_f32_e32 v109, v109
	v_cvt_pk_bf16_f32 v160, v100, v101
	v_cvt_pk_bf16_f32 v161, v102, v103
	v_add_f32_e32 v141, v141, v102
	v_add_f32_e32 v150, v150, v103
	v_mfma_f32_32x32x16_bf16 v[16:31], v[186:189], v[162:165], v[16:31]
	ds_read_b128 v[174:177], v146 offset:8192
	ds_read_b128 v[178:181], v147 offset:8192
	ds_read_b128 v[182:185], v146 offset:12288
	ds_read_b128 v[186:189], v147 offset:12288
	v_exp_f32_e32 v110, v110
	v_exp_f32_e32 v111, v111
	v_add_f32_e32 v141, v141, v104
	v_add_f32_e32 v150, v150, v105
	v_add_f32_e32 v141, v141, v106
	v_add_f32_e32 v150, v150, v107
	v_add_f32_e32 v141, v141, v108
	v_add_f32_e32 v150, v150, v109
	v_cvt_pk_bf16_f32 v162, v104, v105
	v_cvt_pk_bf16_f32 v163, v106, v107
	v_cvt_pk_bf16_f32 v164, v108, v109
	v_add_f32_e32 v141, v141, v110
	v_add_f32_e32 v150, v150, v111
	v_cvt_pk_bf16_f32 v165, v110, v111
	s_waitcnt lgkmcnt(4)
	v_mfma_f32_32x32x16_bf16 v[96:111], v[166:169], v[112:115], v[48:63]
	v_exp_f32_e32 v116, v116
	v_exp_f32_e32 v117, v117
	v_exp_f32_e32 v118, v118
	v_exp_f32_e32 v119, v119
	v_mfma_f32_32x32x16_bf16 v[96:111], v[170:173], v[42:45], v[96:111]
	v_exp_f32_e32 v120, v120
	v_exp_f32_e32 v121, v121
	v_exp_f32_e32 v122, v122
	v_exp_f32_e32 v123, v123
	ds_read_b128 v[166:169], v148 offset:4096
	ds_read_b128 v[170:173], v149 offset:4096
	s_waitcnt lgkmcnt(2)
	v_mfma_f32_32x32x16_bf16 v[64:79], v[174:177], v[158:161], v[64:79]
	v_exp_f32_e32 v124, v124
	v_exp_f32_e32 v125, v125
	v_add_f32_e32 v140, v140, v116
	v_add_f32_e32 v151, v151, v117
	v_add_f32_e32 v140, v140, v118
	v_add_f32_e32 v151, v151, v119
	v_mfma_f32_32x32x16_bf16 v[0:15], v[182:185], v[158:161], v[0:15]
	v_exp_f32_e32 v126, v126
	v_exp_f32_e32 v127, v127
	v_cvt_pk_bf16_f32 v158, v116, v117
	v_cvt_pk_bf16_f32 v159, v118, v119
	v_add_f32_e32 v140, v140, v120
	v_add_f32_e32 v151, v151, v121
	v_mfma_f32_32x32x16_bf16 v[64:79], v[178:181], v[162:165], v[64:79]
	v_exp_f32_e32 v128, v128
	v_exp_f32_e32 v129, v129
	v_cvt_pk_bf16_f32 v160, v120, v121
	v_cvt_pk_bf16_f32 v161, v122, v123
	v_add_f32_e32 v140, v140, v122
	v_add_f32_e32 v151, v151, v123
	v_mfma_f32_32x32x16_bf16 v[0:15], v[186:189], v[162:165], v[0:15]
	v_exp_f32_e32 v130, v130
	v_exp_f32_e32 v131, v131
	v_add_f32_e32 v140, v140, v124
	v_add_f32_e32 v151, v151, v125
	v_add_f32_e32 v140, v140, v126
	v_add_f32_e32 v151, v151, v127
	v_add_f32_e32 v140, v140, v128
	v_add_f32_e32 v151, v151, v129
	v_cvt_pk_bf16_f32 v162, v124, v125
	v_cvt_pk_bf16_f32 v163, v126, v127
	v_cvt_pk_bf16_f32 v164, v128, v129
	v_add_f32_e32 v140, v140, v130
	v_add_f32_e32 v151, v151, v131
	v_cvt_pk_bf16_f32 v165, v130, v131
	s_waitcnt lgkmcnt(0)
	v_mfma_f32_32x32x16_bf16 v[116:131], v[166:169], v[38:41], v[48:63]
	v_exp_f32_e32 v96, v96
	v_exp_f32_e32 v97, v97
	v_exp_f32_e32 v98, v98
	v_exp_f32_e32 v99, v99
	v_mfma_f32_32x32x16_bf16 v[116:131], v[170:173], v[34:37], v[116:131]
	v_exp_f32_e32 v100, v100
	v_exp_f32_e32 v101, v101
	v_exp_f32_e32 v102, v102
	v_exp_f32_e32 v103, v103
	ds_read_b128 v[166:169], v146 offset:16384
	ds_read_b128 v[170:173], v147 offset:16384
	v_mfma_f32_32x32x16_bf16 v[80:95], v[174:177], v[158:161], v[80:95]
	v_exp_f32_e32 v104, v104
	v_exp_f32_e32 v105, v105
	v_add_f32_e32 v141, v141, v96
	v_add_f32_e32 v150, v150, v97
	v_add_f32_e32 v141, v141, v98
	v_add_f32_e32 v150, v150, v99
	v_mfma_f32_32x32x16_bf16 v[16:31], v[182:185], v[158:161], v[16:31]
	v_exp_f32_e32 v106, v106
	v_exp_f32_e32 v107, v107
	v_cvt_pk_bf16_f32 v158, v96, v97
	v_cvt_pk_bf16_f32 v159, v98, v99
	v_add_f32_e32 v141, v141, v100
	v_add_f32_e32 v150, v150, v101
	v_mfma_f32_32x32x16_bf16 v[80:95], v[178:181], v[162:165], v[80:95]
	v_exp_f32_e32 v108, v108
	v_exp_f32_e32 v109, v109
	v_cvt_pk_bf16_f32 v160, v100, v101
	v_cvt_pk_bf16_f32 v161, v102, v103
	v_add_f32_e32 v141, v141, v102
	v_add_f32_e32 v150, v150, v103
	v_mfma_f32_32x32x16_bf16 v[16:31], v[186:189], v[162:165], v[16:31]
	ds_read_b128 v[174:177], v148 offset:8192
	ds_read_b128 v[178:181], v149 offset:8192
	ds_read_b128 v[182:185], v148 offset:12288
	ds_read_b128 v[186:189], v149 offset:12288
	v_exp_f32_e32 v110, v110
	v_exp_f32_e32 v111, v111
	v_add_f32_e32 v141, v141, v104
	v_add_f32_e32 v150, v150, v105
	v_add_f32_e32 v141, v141, v106
	v_add_f32_e32 v150, v150, v107
	v_add_f32_e32 v141, v141, v108
	v_add_f32_e32 v150, v150, v109
	v_cvt_pk_bf16_f32 v162, v104, v105
	v_cvt_pk_bf16_f32 v163, v106, v107
	v_cvt_pk_bf16_f32 v164, v108, v109
	v_add_f32_e32 v141, v141, v110
	v_add_f32_e32 v150, v150, v111
	v_cvt_pk_bf16_f32 v165, v110, v111
	s_waitcnt lgkmcnt(4)
; DI float ex2(float x) { return __builtin_amdgcn_exp2f(x); }
; #define MFMA32(a, b, c) __builtin_amdgcn_mfma_f32_32x32x16_bf16((a), (b), (c), 0, 0, 0)
; template <int MODE>
; DI void attn_unit(unsigned char* lds, const AttnParams& ap, int b, int h, int qb, int tid) {
;     ...
;     for (int c = 0; c < NCH; ++c) { *(u32x4*)(Ks0 + (c * 64 + lrow) * 72 + 8 * lch) = kreg[c]; *(u32x4*)(Vs0 + (c * 64 + lrow) * 72 + 8 * lch) = vreg[c]; }
;     __syncthreads();
;     if (n + NCH < ntiles) {
; #pragma unroll
;       for (int c = 0; c < NCH; ++c) { const int jn = (MODE == 2) ? jb - NCH - c : jb + NCH + c; kreg[c] = *(const u32x4*)(kg + (size_t)jn * 64 * PLD); vreg[c] = *(const u32x4*)(vg + (size_t)jn * 4096); } }
; #pragma unroll
;     for (int c = 0; c < NCH; ++c) {
;     const int j = (MODE == 2) ? jb - c : jb + c;
;     const bf16_t* Ks = Ks0 + c * 64 * 72; const bf16_t* Vs = Vs0 + c * 64 * 72;
;     const bool active = (j <= cw) && (MODE != 0 || j >= cw - 8);
;     if (!active) continue;
;     if (MODE == 2 && D_EARLY && wdone) continue;
;     if (MODE == 1) {
; #pragma unroll
;       for (int kh = 0; kh < 2; ++kh) {
;         const bf16_t* kb = Ks + (32 * kh + r32) * 72 + 8 * hi;
;         bf16x8 p0[2], p1[2];
;         { f32x16 s0 = splat16(ap.negM);
;           s0 = MFMA32(*(const bf16x8*)(kb), qf[0], s0); s0 = MFMA32(*(const bf16x8*)(kb + 16), qf[1], s0);
; #pragma unroll
;           for (int i = 0; i < 16; ++i) { s0[i] = ex2(s0[i]); l0 += s0[i]; }
;           p0[0] = pack8(s0, 0); p0[1] = pack8(s0, 1); }
;         { f32x16 s1 = splat16(ap.negM);
;           s1 = MFMA32(*(const bf16x8*)(kb + 32), qf[2], s1); s1 = MFMA32(*(const bf16x8*)(kb + 48), qf[3], s1);
; #pragma unroll
;           for (int i = 0; i < 16; ++i) { s1[i] = ex2(s1[i]); l1 += s1[i]; }
;           p1[0] = pack8(s1, 0); p1[1] = pack8(s1, 1); }
; #pragma unroll
;         for (int kk = 0; kk < 2; ++kk) {
; #pragma unroll
;           for (int eb = 0; eb < 2; ++eb) { const bf16_t* vb = Vs + (32 * eb + r32) * 72 + 32 * kh + 16 * kk + 8 * hi; const bf16x8 vf = *(const bf16x8*)vb;
;             O0[eb] = MFMA32(vf, p0[kk], O0[eb]); O1[eb] = MFMA32(vf, p1[kk], O1[eb]); } }
	v_mfma_f32_32x32x16_bf16 v[96:111], v[166:169], v[112:115], v[48:63]
	v_exp_f32_e32 v116, v116
	v_exp_f32_e32 v117, v117
	v_exp_f32_e32 v118, v118
	v_exp_f32_e32 v119, v119
	v_mfma_f32_32x32x16_bf16 v[96:111], v[170:173], v[42:45], v[96:111]
	v_exp_f32_e32 v120, v120
	v_exp_f32_e32 v121, v121
	v_exp_f32_e32 v122, v122
	v_exp_f32_e32 v123, v123
	ds_read_b128 v[166:169], v148 offset:16384
	ds_read_b128 v[170:173], v149 offset:16384
	s_waitcnt lgkmcnt(2)
	v_mfma_f32_32x32x16_bf16 v[64:79], v[174:177], v[158:161], v[64:79]
	v_exp_f32_e32 v124, v124
	v_exp_f32_e32 v125, v125
	v_add_f32_e32 v140, v140, v116
	v_add_f32_e32 v151, v151, v117
	v_add_f32_e32 v140, v140, v118
	v_add_f32_e32 v151, v151, v119
	v_mfma_f32_32x32x16_bf16 v[0:15], v[182:185], v[158:161], v[0:15]
	v_exp_f32_e32 v126, v126
	v_exp_f32_e32 v127, v127
	v_cvt_pk_bf16_f32 v158, v116, v117
	v_cvt_pk_bf16_f32 v159, v118, v119
	v_add_f32_e32 v140, v140, v120
	v_add_f32_e32 v151, v151, v121
	v_mfma_f32_32x32x16_bf16 v[64:79], v[178:181], v[162:165], v[64:79]
	v_exp_f32_e32 v128, v128
	v_exp_f32_e32 v129, v129
	v_cvt_pk_bf16_f32 v160, v120, v121
	v_cvt_pk_bf16_f32 v161, v122, v123
	v_add_f32_e32 v140, v140, v122
	v_add_f32_e32 v151, v151, v123
	v_mfma_f32_32x32x16_bf16 v[0:15], v[186:189], v[162:165], v[0:15]
	v_exp_f32_e32 v130, v130
	v_exp_f32_e32 v131, v131
	v_add_f32_e32 v140, v140, v124
	v_add_f32_e32 v151, v151, v125
	v_add_f32_e32 v140, v140, v126
	v_add_f32_e32 v151, v151, v127
	v_add_f32_e32 v140, v140, v128
	v_add_f32_e32 v151, v151, v129
	v_cvt_pk_bf16_f32 v162, v124, v125
	v_cvt_pk_bf16_f32 v163, v126, v127
	v_cvt_pk_bf16_f32 v164, v128, v129
	v_add_f32_e32 v140, v140, v130
	v_add_f32_e32 v151, v151, v131
	v_cvt_pk_bf16_f32 v165, v130, v131
	s_add_i32 s4, s4, 1
	s_waitcnt vmcnt(0) lgkmcnt(0)
	s_barrier
	s_nop 0
	s_barrier
	s_cmp_le_u32 s4, s5
	s_cbranch_scc1 .Lc_tile_ph1
	s_mov_b32 s9, 1
	s_branch .Lc_drain
.Lc_tile_ph1:
	s_add_i32 m0, s0, 0
	s_nop 0
	global_load_lds_dwordx4 v32, s[2:3]
	s_add_i32 m0, s0, 8192
	s_nop 0
	global_load_lds_dwordx4 v157, s[10:11]
	s_add_u32 s2, s2, 0x68800
	s_addc_u32 s3, s3, 0
	s_add_u32 s10, s10, 0x2000
	s_addc_u32 s11, s11, 0
	s_waitcnt lgkmcnt(0)
	v_mfma_f32_32x32x16_bf16 v[116:131], v[166:169], v[38:41], v[48:63]
	v_exp_f32_e32 v96, v96
	v_exp_f32_e32 v97, v97
	v_exp_f32_e32 v98, v98
	v_exp_f32_e32 v99, v99
	v_mfma_f32_32x32x16_bf16 v[116:131], v[170:173], v[34:37], v[116:131]
	v_exp_f32_e32 v100, v100
	v_exp_f32_e32 v101, v101
	v_exp_f32_e32 v102, v102
	v_exp_f32_e32 v103, v103
	ds_read_b128 v[166:169], v146 offset:20480
	ds_read_b128 v[170:173], v147 offset:20480
	v_mfma_f32_32x32x16_bf16 v[80:95], v[174:177], v[158:161], v[80:95]
	v_exp_f32_e32 v104, v104
	v_exp_f32_e32 v105, v105
	v_add_f32_e32 v141, v141, v96
	v_add_f32_e32 v150, v150, v97
	v_add_f32_e32 v141, v141, v98
	v_add_f32_e32 v150, v150, v99
	v_mfma_f32_32x32x16_bf16 v[16:31], v[182:185], v[158:161], v[16:31]
	v_exp_f32_e32 v106, v106
	v_exp_f32_e32 v107, v107
	v_cvt_pk_bf16_f32 v158, v96, v97
	v_cvt_pk_bf16_f32 v159, v98, v99
	v_add_f32_e32 v141, v141, v100
	v_add_f32_e32 v150, v150, v101
	v_mfma_f32_32x32x16_bf16 v[80:95], v[178:181], v[162:165], v[80:95]
	v_exp_f32_e32 v108, v108
	v_exp_f32_e32 v109, v109
	v_cvt_pk_bf16_f32 v160, v100, v101
	v_cvt_pk_bf16_f32 v161, v102, v103
	v_add_f32_e32 v141, v141, v102
	v_add_f32_e32 v150, v150, v103
	v_mfma_f32_32x32x16_bf16 v[16:31], v[186:189], v[162:165], v[16:31]
	ds_read_b128 v[174:177], v146 offset:24576
	ds_read_b128 v[178:181], v147 offset:24576
	ds_read_b128 v[182:185], v146 offset:28672
	ds_read_b128 v[186:189], v147 offset:28672
	v_exp_f32_e32 v110, v110
	v_exp_f32_e32 v111, v111
	v_add_f32_e32 v141, v141, v104
	v_add_f32_e32 v150, v150, v105
	v_add_f32_e32 v141, v141, v106
	v_add_f32_e32 v150, v150, v107
	v_add_f32_e32 v141, v141, v108
	v_add_f32_e32 v150, v150, v109
	v_cvt_pk_bf16_f32 v162, v104, v105
	v_cvt_pk_bf16_f32 v163, v106, v107
	v_cvt_pk_bf16_f32 v164, v108, v109
	v_add_f32_e32 v141, v141, v110
	v_add_f32_e32 v150, v150, v111
	v_cvt_pk_bf16_f32 v165, v110, v111
	s_waitcnt lgkmcnt(4)
	v_mfma_f32_32x32x16_bf16 v[96:111], v[166:169], v[112:115], v[48:63]
	v_exp_f32_e32 v116, v116
	v_exp_f32_e32 v117, v117
	v_exp_f32_e32 v118, v118
	v_exp_f32_e32 v119, v119
	v_mfma_f32_32x32x16_bf16 v[96:111], v[170:173], v[42:45], v[96:111]
	v_exp_f32_e32 v120, v120
	v_exp_f32_e32 v121, v121
	v_exp_f32_e32 v122, v122
	v_exp_f32_e32 v123, v123
	ds_read_b128 v[166:169], v148 offset:20480
	ds_read_b128 v[170:173], v149 offset:20480
	s_waitcnt lgkmcnt(2)
	v_mfma_f32_32x32x16_bf16 v[64:79], v[174:177], v[158:161], v[64:79]
	v_exp_f32_e32 v124, v124
	v_exp_f32_e32 v125, v125
	v_add_f32_e32 v140, v140, v116
	v_add_f32_e32 v151, v151, v117
	v_add_f32_e32 v140, v140, v118
	v_add_f32_e32 v151, v151, v119
	v_mfma_f32_32x32x16_bf16 v[0:15], v[182:185], v[158:161], v[0:15]
	v_exp_f32_e32 v126, v126
	v_exp_f32_e32 v127, v127
	v_cvt_pk_bf16_f32 v158, v116, v117
	v_cvt_pk_bf16_f32 v159, v118, v119
	v_add_f32_e32 v140, v140, v120
	v_add_f32_e32 v151, v151, v121
	v_mfma_f32_32x32x16_bf16 v[64:79], v[178:181], v[162:165], v[64:79]
	v_exp_f32_e32 v128, v128
	v_exp_f32_e32 v129, v129
	v_cvt_pk_bf16_f32 v160, v120, v121
	v_cvt_pk_bf16_f32 v161, v122, v123
	v_add_f32_e32 v140, v140, v122
	v_add_f32_e32 v151, v151, v123
	v_mfma_f32_32x32x16_bf16 v[0:15], v[186:189], v[162:165], v[0:15]
	v_exp_f32_e32 v130, v130
	v_exp_f32_e32 v131, v131
	v_add_f32_e32 v140, v140, v124
	v_add_f32_e32 v151, v151, v125
	v_add_f32_e32 v140, v140, v126
	v_add_f32_e32 v151, v151, v127
	v_add_f32_e32 v140, v140, v128
	v_add_f32_e32 v151, v151, v129
	v_cvt_pk_bf16_f32 v162, v124, v125
	v_cvt_pk_bf16_f32 v163, v126, v127
	v_cvt_pk_bf16_f32 v164, v128, v129
	v_add_f32_e32 v140, v140, v130
	v_add_f32_e32 v151, v151, v131
	v_cvt_pk_bf16_f32 v165, v130, v131
	s_waitcnt lgkmcnt(0)
; DI float ex2(float x) { return __builtin_amdgcn_exp2f(x); }
; #define MFMA32(a, b, c) __builtin_amdgcn_mfma_f32_32x32x16_bf16((a), (b), (c), 0, 0, 0)
; template <int MODE>
; DI void attn_unit(unsigned char* lds, const AttnParams& ap, int b, int h, int qb, int tid) {
;     ...
;   for (int n = 0; n < ntiles; n += NCH) {
;     const int jb = (MODE == 2) ? jhi - n : jlo + n;
;     __syncthreads();
;     if (MODE == 2 && D_EARLY) { int alld = 1;
; #pragma unroll
;       for (int w = 0; w < 8; ++w) alld &= flags[w];
;       if (alld) break; }
; #pragma unroll
;     for (int c = 0; c < NCH; ++c) { *(u32x4*)(Ks0 + (c * 64 + lrow) * 72 + 8 * lch) = kreg[c]; *(u32x4*)(Vs0 + (c * 64 + lrow) * 72 + 8 * lch) = vreg[c]; }
;     __syncthreads();
;     if (n + NCH < ntiles) {
; #pragma unroll
;       for (int c = 0; c < NCH; ++c) { const int jn = (MODE == 2) ? jb - NCH - c : jb + NCH + c; kreg[c] = *(const u32x4*)(kg + (size_t)jn * 64 * PLD); vreg[c] = *(const u32x4*)(vg + (size_t)jn * 4096); } }
;     ...
;       for (int kh = 0; kh < 2; ++kh) {
;         const bf16_t* kb = Ks + (32 * kh + r32) * 72 + 8 * hi;
;         bf16x8 p0[2], p1[2];
;         { f32x16 s0 = splat16(ap.negM);
;           s0 = MFMA32(*(const bf16x8*)(kb), qf[0], s0); s0 = MFMA32(*(const bf16x8*)(kb + 16), qf[1], s0);
; #pragma unroll
;           for (int i = 0; i < 16; ++i) { s0[i] = ex2(s0[i]); l0 += s0[i]; }
;           p0[0] = pack8(s0, 0); p0[1] = pack8(s0, 1); }
;         { f32x16 s1 = splat16(ap.negM);
;           s1 = MFMA32(*(const bf16x8*)(kb + 32), qf[2], s1); s1 = MFMA32(*(const bf16x8*)(kb + 48), qf[3], s1);
; #pragma unroll
;           for (int i = 0; i < 16; ++i) { s1[i] = ex2(s1[i]); l1 += s1[i]; }
;           p1[0] = pack8(s1, 0); p1[1] = pack8(s1, 1); }
; #pragma unroll
;         for (int kk = 0; kk < 2; ++kk) {
; #pragma unroll
;           for (int eb = 0; eb < 2; ++eb) { const bf16_t* vb = Vs + (32 * eb + r32) * 72 + 32 * kh + 16 * kk + 8 * hi; const bf16x8 vf = *(const bf16x8*)vb;
;             O0[eb] = MFMA32(vf, p0[kk], O0[eb]); O1[eb] = MFMA32(vf, p1[kk], O1[eb]); } }
	v_mfma_f32_32x32x16_bf16 v[116:131], v[166:169], v[38:41], v[48:63]
	v_exp_f32_e32 v96, v96
	v_exp_f32_e32 v97, v97
	v_exp_f32_e32 v98, v98
	v_exp_f32_e32 v99, v99
	v_mfma_f32_32x32x16_bf16 v[116:131], v[170:173], v[34:37], v[116:131]
	v_exp_f32_e32 v100, v100
	v_exp_f32_e32 v101, v101
	v_exp_f32_e32 v102, v102
	v_exp_f32_e32 v103, v103
	ds_read_b128 v[166:169], v146 offset:32768
	ds_read_b128 v[170:173], v147 offset:32768
	v_mfma_f32_32x32x16_bf16 v[80:95], v[174:177], v[158:161], v[80:95]
	v_exp_f32_e32 v104, v104
	v_exp_f32_e32 v105, v105
	v_add_f32_e32 v141, v141, v96
	v_add_f32_e32 v150, v150, v97
	v_add_f32_e32 v141, v141, v98
	v_add_f32_e32 v150, v150, v99
	v_mfma_f32_32x32x16_bf16 v[16:31], v[182:185], v[158:161], v[16:31]
	v_exp_f32_e32 v106, v106
	v_exp_f32_e32 v107, v107
	v_cvt_pk_bf16_f32 v158, v96, v97
	v_cvt_pk_bf16_f32 v159, v98, v99
	v_add_f32_e32 v141, v141, v100
	v_add_f32_e32 v150, v150, v101
	v_mfma_f32_32x32x16_bf16 v[80:95], v[178:181], v[162:165], v[80:95]
	v_exp_f32_e32 v108, v108
	v_exp_f32_e32 v109, v109
	v_cvt_pk_bf16_f32 v160, v100, v101
	v_cvt_pk_bf16_f32 v161, v102, v103
	v_add_f32_e32 v141, v141, v102
	v_add_f32_e32 v150, v150, v103
	v_mfma_f32_32x32x16_bf16 v[16:31], v[186:189], v[162:165], v[16:31]
	ds_read_b128 v[174:177], v148 offset:24576
	ds_read_b128 v[178:181], v149 offset:24576
	ds_read_b128 v[182:185], v148 offset:28672
	ds_read_b128 v[186:189], v149 offset:28672
	v_exp_f32_e32 v110, v110
	v_exp_f32_e32 v111, v111
	v_add_f32_e32 v141, v141, v104
	v_add_f32_e32 v150, v150, v105
	v_add_f32_e32 v141, v141, v106
	v_add_f32_e32 v150, v150, v107
	v_add_f32_e32 v141, v141, v108
	v_add_f32_e32 v150, v150, v109
	v_cvt_pk_bf16_f32 v162, v104, v105
	v_cvt_pk_bf16_f32 v163, v106, v107
	v_cvt_pk_bf16_f32 v164, v108, v109
	v_add_f32_e32 v141, v141, v110
	v_add_f32_e32 v150, v150, v111
	v_cvt_pk_bf16_f32 v165, v110, v111
	s_waitcnt lgkmcnt(4)
	v_mfma_f32_32x32x16_bf16 v[96:111], v[166:169], v[112:115], v[48:63]
	v_exp_f32_e32 v116, v116
	v_exp_f32_e32 v117, v117
	v_exp_f32_e32 v118, v118
	v_exp_f32_e32 v119, v119
	v_mfma_f32_32x32x16_bf16 v[96:111], v[170:173], v[42:45], v[96:111]
	v_exp_f32_e32 v120, v120
	v_exp_f32_e32 v121, v121
	v_exp_f32_e32 v122, v122
	v_exp_f32_e32 v123, v123
	ds_read_b128 v[166:169], v148 offset:32768
	ds_read_b128 v[170:173], v149 offset:32768
	s_waitcnt lgkmcnt(2)
	v_mfma_f32_32x32x16_bf16 v[64:79], v[174:177], v[158:161], v[64:79]
	v_exp_f32_e32 v124, v124
	v_exp_f32_e32 v125, v125
	v_add_f32_e32 v140, v140, v116
	v_add_f32_e32 v151, v151, v117
	v_add_f32_e32 v140, v140, v118
	v_add_f32_e32 v151, v151, v119
	v_mfma_f32_32x32x16_bf16 v[0:15], v[182:185], v[158:161], v[0:15]
	v_exp_f32_e32 v126, v126
	v_exp_f32_e32 v127, v127
	v_cvt_pk_bf16_f32 v158, v116, v117
	v_cvt_pk_bf16_f32 v159, v118, v119
	v_add_f32_e32 v140, v140, v120
	v_add_f32_e32 v151, v151, v121
	v_mfma_f32_32x32x16_bf16 v[64:79], v[178:181], v[162:165], v[64:79]
	v_exp_f32_e32 v128, v128
	v_exp_f32_e32 v129, v129
	v_cvt_pk_bf16_f32 v160, v120, v121
	v_cvt_pk_bf16_f32 v161, v122, v123
	v_add_f32_e32 v140, v140, v122
	v_add_f32_e32 v151, v151, v123
	v_mfma_f32_32x32x16_bf16 v[0:15], v[186:189], v[162:165], v[0:15]
	v_exp_f32_e32 v130, v130
	v_exp_f32_e32 v131, v131
	v_add_f32_e32 v140, v140, v124
	v_add_f32_e32 v151, v151, v125
	v_add_f32_e32 v140, v140, v126
	v_add_f32_e32 v151, v151, v127
	v_add_f32_e32 v140, v140, v128
	v_add_f32_e32 v151, v151, v129
	v_cvt_pk_bf16_f32 v162, v124, v125
	v_cvt_pk_bf16_f32 v163, v126, v127
	v_cvt_pk_bf16_f32 v164, v128, v129
	v_add_f32_e32 v140, v140, v130
	v_add_f32_e32 v151, v151, v131
	v_cvt_pk_bf16_f32 v165, v130, v131
	s_add_i32 s4, s4, 1
	s_waitcnt vmcnt(0) lgkmcnt(0)
	s_barrier
	s_nop 0
	s_barrier
	s_cmp_le_u32 s4, s5
	s_cbranch_scc1 .Lc_tile_ph2
	s_mov_b32 s9, 2
	s_branch .Lc_drain
.Lc_tile_ph2:
	s_add_i32 m0, s0, 16384
	s_nop 0
	global_load_lds_dwordx4 v32, s[2:3]
	s_add_i32 m0, s0, 24576
	s_nop 0
	global_load_lds_dwordx4 v157, s[10:11]
	s_add_u32 s2, s2, 0x68800
	s_addc_u32 s3, s3, 0
	s_add_u32 s10, s10, 0x2000
	s_addc_u32 s11, s11, 0
	s_waitcnt lgkmcnt(0)
	v_mfma_f32_32x32x16_bf16 v[116:131], v[166:169], v[38:41], v[48:63]
	v_exp_f32_e32 v96, v96
	v_exp_f32_e32 v97, v97
	v_exp_f32_e32 v98, v98
	v_exp_f32_e32 v99, v99
	v_mfma_f32_32x32x16_bf16 v[116:131], v[170:173], v[34:37], v[116:131]
	v_exp_f32_e32 v100, v100
	v_exp_f32_e32 v101, v101
	v_exp_f32_e32 v102, v102
	v_exp_f32_e32 v103, v103
	ds_read_b128 v[166:169], v146 offset:36864
	ds_read_b128 v[170:173], v147 offset:36864
	v_mfma_f32_32x32x16_bf16 v[80:95], v[174:177], v[158:161], v[80:95]
	v_exp_f32_e32 v104, v104
	v_exp_f32_e32 v105, v105
	v_add_f32_e32 v141, v141, v96
	v_add_f32_e32 v150, v150, v97
	v_add_f32_e32 v141, v141, v98
	v_add_f32_e32 v150, v150, v99
	v_mfma_f32_32x32x16_bf16 v[16:31], v[182:185], v[158:161], v[16:31]
	v_exp_f32_e32 v106, v106
	v_exp_f32_e32 v107, v107
	v_cvt_pk_bf16_f32 v158, v96, v97
	v_cvt_pk_bf16_f32 v159, v98, v99
	v_add_f32_e32 v141, v141, v100
	v_add_f32_e32 v150, v150, v101
	v_mfma_f32_32x32x16_bf16 v[80:95], v[178:181], v[162:165], v[80:95]
	v_exp_f32_e32 v108, v108
	v_exp_f32_e32 v109, v109
	v_cvt_pk_bf16_f32 v160, v100, v101
	v_cvt_pk_bf16_f32 v161, v102, v103
	v_add_f32_e32 v141, v141, v102
	v_add_f32_e32 v150, v150, v103
	v_mfma_f32_32x32x16_bf16 v[16:31], v[186:189], v[162:165], v[16:31]
	ds_read_b128 v[174:177], v146 offset:40960
	ds_read_b128 v[178:181], v147 offset:40960
	ds_read_b128 v[182:185], v146 offset:45056
	ds_read_b128 v[186:189], v147 offset:45056
	v_exp_f32_e32 v110, v110
	v_exp_f32_e32 v111, v111
	v_add_f32_e32 v141, v141, v104
	v_add_f32_e32 v150, v150, v105
	v_add_f32_e32 v141, v141, v106
	v_add_f32_e32 v150, v150, v107
	v_add_f32_e32 v141, v141, v108
	v_add_f32_e32 v150, v150, v109
	v_cvt_pk_bf16_f32 v162, v104, v105
	v_cvt_pk_bf16_f32 v163, v106, v107
	v_cvt_pk_bf16_f32 v164, v108, v109
	v_add_f32_e32 v141, v141, v110
	v_add_f32_e32 v150, v150, v111
	v_cvt_pk_bf16_f32 v165, v110, v111
	s_waitcnt lgkmcnt(4)
; DI float ex2(float x) { return __builtin_amdgcn_exp2f(x); }
; #define MFMA32(a, b, c) __builtin_amdgcn_mfma_f32_32x32x16_bf16((a), (b), (c), 0, 0, 0)
; template <int MODE>
; DI void attn_unit(unsigned char* lds, const AttnParams& ap, int b, int h, int qb, int tid) {
;     ...
;   for (int n = 0; n < ntiles; n += NCH) {
;     const int jb = (MODE == 2) ? jhi - n : jlo + n;
;     __syncthreads();
;     if (MODE == 2 && D_EARLY) { int alld = 1;
; #pragma unroll
;       for (int w = 0; w < 8; ++w) alld &= flags[w];
;       if (alld) break; }
; #pragma unroll
;     for (int c = 0; c < NCH; ++c) { *(u32x4*)(Ks0 + (c * 64 + lrow) * 72 + 8 * lch) = kreg[c]; *(u32x4*)(Vs0 + (c * 64 + lrow) * 72 + 8 * lch) = vreg[c]; }
;     __syncthreads();
;     if (n + NCH < ntiles) {
; #pragma unroll
;       for (int c = 0; c < NCH; ++c) { const int jn = (MODE == 2) ? jb - NCH - c : jb + NCH + c; kreg[c] = *(const u32x4*)(kg + (size_t)jn * 64 * PLD); vreg[c] = *(const u32x4*)(vg + (size_t)jn * 4096); } }
;     ...
;       for (int kh = 0; kh < 2; ++kh) {
;         const bf16_t* kb = Ks + (32 * kh + r32) * 72 + 8 * hi;
;         bf16x8 p0[2], p1[2];
;         { f32x16 s0 = splat16(ap.negM);
;           s0 = MFMA32(*(const bf16x8*)(kb), qf[0], s0); s0 = MFMA32(*(const bf16x8*)(kb + 16), qf[1], s0);
; #pragma unroll
;           for (int i = 0; i < 16; ++i) { s0[i] = ex2(s0[i]); l0 += s0[i]; }
;           p0[0] = pack8(s0, 0); p0[1] = pack8(s0, 1); }
;         { f32x16 s1 = splat16(ap.negM);
;           s1 = MFMA32(*(const bf16x8*)(kb + 32), qf[2], s1); s1 = MFMA32(*(const bf16x8*)(kb + 48), qf[3], s1);
; #pragma unroll
;           for (int i = 0; i < 16; ++i) { s1[i] = ex2(s1[i]); l1 += s1[i]; }
;           p1[0] = pack8(s1, 0); p1[1] = pack8(s1, 1); }
; #pragma unroll
;         for (int kk = 0; kk < 2; ++kk) {
; #pragma unroll
;           for (int eb = 0; eb < 2; ++eb) { const bf16_t* vb = Vs + (32 * eb + r32) * 72 + 32 * kh + 16 * kk + 8 * hi; const bf16x8 vf = *(const bf16x8*)vb;
;             O0[eb] = MFMA32(vf, p0[kk], O0[eb]); O1[eb] = MFMA32(vf, p1[kk], O1[eb]); } }
	v_mfma_f32_32x32x16_bf16 v[96:111], v[166:169], v[112:115], v[48:63]
	v_exp_f32_e32 v116, v116
	v_exp_f32_e32 v117, v117
	v_exp_f32_e32 v118, v118
	v_exp_f32_e32 v119, v119
	v_mfma_f32_32x32x16_bf16 v[96:111], v[170:173], v[42:45], v[96:111]
	v_exp_f32_e32 v120, v120
	v_exp_f32_e32 v121, v121
	v_exp_f32_e32 v122, v122
	v_exp_f32_e32 v123, v123
	ds_read_b128 v[166:169], v148 offset:36864
	ds_read_b128 v[170:173], v149 offset:36864
	s_waitcnt lgkmcnt(2)
	v_mfma_f32_32x32x16_bf16 v[64:79], v[174:177], v[158:161], v[64:79]
	v_exp_f32_e32 v124, v124
	v_exp_f32_e32 v125, v125
	v_add_f32_e32 v140, v140, v116
	v_add_f32_e32 v151, v151, v117
	v_add_f32_e32 v140, v140, v118
	v_add_f32_e32 v151, v151, v119
	v_mfma_f32_32x32x16_bf16 v[0:15], v[182:185], v[158:161], v[0:15]
	v_exp_f32_e32 v126, v126
	v_exp_f32_e32 v127, v127
	v_cvt_pk_bf16_f32 v158, v116, v117
	v_cvt_pk_bf16_f32 v159, v118, v119
	v_add_f32_e32 v140, v140, v120
	v_add_f32_e32 v151, v151, v121
	v_mfma_f32_32x32x16_bf16 v[64:79], v[178:181], v[162:165], v[64:79]
	v_exp_f32_e32 v128, v128
	v_exp_f32_e32 v129, v129
	v_cvt_pk_bf16_f32 v160, v120, v121
	v_cvt_pk_bf16_f32 v161, v122, v123
	v_add_f32_e32 v140, v140, v122
	v_add_f32_e32 v151, v151, v123
	v_mfma_f32_32x32x16_bf16 v[0:15], v[186:189], v[162:165], v[0:15]
	v_exp_f32_e32 v130, v130
	v_exp_f32_e32 v131, v131
	v_add_f32_e32 v140, v140, v124
	v_add_f32_e32 v151, v151, v125
	v_add_f32_e32 v140, v140, v126
	v_add_f32_e32 v151, v151, v127
	v_add_f32_e32 v140, v140, v128
	v_add_f32_e32 v151, v151, v129
	v_cvt_pk_bf16_f32 v162, v124, v125
	v_cvt_pk_bf16_f32 v163, v126, v127
	v_cvt_pk_bf16_f32 v164, v128, v129
	v_add_f32_e32 v140, v140, v130
	v_add_f32_e32 v151, v151, v131
	v_cvt_pk_bf16_f32 v165, v130, v131
	s_waitcnt lgkmcnt(0)
	v_mfma_f32_32x32x16_bf16 v[116:131], v[166:169], v[38:41], v[48:63]
	v_exp_f32_e32 v96, v96
	v_exp_f32_e32 v97, v97
	v_exp_f32_e32 v98, v98
	v_exp_f32_e32 v99, v99
	v_mfma_f32_32x32x16_bf16 v[116:131], v[170:173], v[34:37], v[116:131]
	v_exp_f32_e32 v100, v100
	v_exp_f32_e32 v101, v101
	v_exp_f32_e32 v102, v102
	v_exp_f32_e32 v103, v103
	ds_read_b128 v[166:169], v146
	ds_read_b128 v[170:173], v147
	v_mfma_f32_32x32x16_bf16 v[80:95], v[174:177], v[158:161], v[80:95]
	v_exp_f32_e32 v104, v104
	v_exp_f32_e32 v105, v105
	v_add_f32_e32 v141, v141, v96
	v_add_f32_e32 v150, v150, v97
	v_add_f32_e32 v141, v141, v98
	v_add_f32_e32 v150, v150, v99
	v_mfma_f32_32x32x16_bf16 v[16:31], v[182:185], v[158:161], v[16:31]
	v_exp_f32_e32 v106, v106
	v_exp_f32_e32 v107, v107
	v_cvt_pk_bf16_f32 v158, v96, v97
	v_cvt_pk_bf16_f32 v159, v98, v99
	v_add_f32_e32 v141, v141, v100
	v_add_f32_e32 v150, v150, v101
	v_mfma_f32_32x32x16_bf16 v[80:95], v[178:181], v[162:165], v[80:95]
	v_exp_f32_e32 v108, v108
	v_exp_f32_e32 v109, v109
	v_cvt_pk_bf16_f32 v160, v100, v101
	v_cvt_pk_bf16_f32 v161, v102, v103
	v_add_f32_e32 v141, v141, v102
	v_add_f32_e32 v150, v150, v103
	v_mfma_f32_32x32x16_bf16 v[16:31], v[186:189], v[162:165], v[16:31]
	ds_read_b128 v[174:177], v148 offset:40960
	ds_read_b128 v[178:181], v149 offset:40960
	ds_read_b128 v[182:185], v148 offset:45056
	ds_read_b128 v[186:189], v149 offset:45056
	v_exp_f32_e32 v110, v110
	v_exp_f32_e32 v111, v111
	v_add_f32_e32 v141, v141, v104
	v_add_f32_e32 v150, v150, v105
	v_add_f32_e32 v141, v141, v106
	v_add_f32_e32 v150, v150, v107
	v_add_f32_e32 v141, v141, v108
	v_add_f32_e32 v150, v150, v109
	v_cvt_pk_bf16_f32 v162, v104, v105
	v_cvt_pk_bf16_f32 v163, v106, v107
	v_cvt_pk_bf16_f32 v164, v108, v109
	v_add_f32_e32 v141, v141, v110
	v_add_f32_e32 v150, v150, v111
	v_cvt_pk_bf16_f32 v165, v110, v111
	s_waitcnt lgkmcnt(4)
	v_mfma_f32_32x32x16_bf16 v[96:111], v[166:169], v[112:115], v[48:63]
	v_exp_f32_e32 v116, v116
	v_exp_f32_e32 v117, v117
	v_exp_f32_e32 v118, v118
	v_exp_f32_e32 v119, v119
	v_mfma_f32_32x32x16_bf16 v[96:111], v[170:173], v[42:45], v[96:111]
	v_exp_f32_e32 v120, v120
	v_exp_f32_e32 v121, v121
	v_exp_f32_e32 v122, v122
	v_exp_f32_e32 v123, v123
	ds_read_b128 v[166:169], v148
	ds_read_b128 v[170:173], v149
	s_waitcnt lgkmcnt(2)
	v_mfma_f32_32x32x16_bf16 v[64:79], v[174:177], v[158:161], v[64:79]
	v_exp_f32_e32 v124, v124
	v_exp_f32_e32 v125, v125
	v_add_f32_e32 v140, v140, v116
	v_add_f32_e32 v151, v151, v117
	v_add_f32_e32 v140, v140, v118
	v_add_f32_e32 v151, v151, v119
	v_mfma_f32_32x32x16_bf16 v[0:15], v[182:185], v[158:161], v[0:15]
	v_exp_f32_e32 v126, v126
	v_exp_f32_e32 v127, v127
	v_cvt_pk_bf16_f32 v158, v116, v117
	v_cvt_pk_bf16_f32 v159, v118, v119
	v_add_f32_e32 v140, v140, v120
	v_add_f32_e32 v151, v151, v121
	v_mfma_f32_32x32x16_bf16 v[64:79], v[178:181], v[162:165], v[64:79]
	v_exp_f32_e32 v128, v128
	v_exp_f32_e32 v129, v129
	v_cvt_pk_bf16_f32 v160, v120, v121
	v_cvt_pk_bf16_f32 v161, v122, v123
	v_add_f32_e32 v140, v140, v122
	v_add_f32_e32 v151, v151, v123
	v_mfma_f32_32x32x16_bf16 v[0:15], v[186:189], v[162:165], v[0:15]
	v_exp_f32_e32 v130, v130
	v_exp_f32_e32 v131, v131
	v_add_f32_e32 v140, v140, v124
	v_add_f32_e32 v151, v151, v125
	v_add_f32_e32 v140, v140, v126
	v_add_f32_e32 v151, v151, v127
	v_add_f32_e32 v140, v140, v128
	v_add_f32_e32 v151, v151, v129
	v_cvt_pk_bf16_f32 v162, v124, v125
	v_cvt_pk_bf16_f32 v163, v126, v127
	v_cvt_pk_bf16_f32 v164, v128, v129
	v_add_f32_e32 v140, v140, v130
	v_add_f32_e32 v151, v151, v131
	v_cvt_pk_bf16_f32 v165, v130, v131
	s_add_i32 s4, s4, 1
	s_waitcnt vmcnt(0) lgkmcnt(0)
	s_barrier
	s_nop 0
	s_barrier
	s_cmp_le_u32 s4, s5
	s_cbranch_scc1 .Lc_tile_ph0
	s_mov_b32 s9, 0
